# passC walk batched loads + flat->global memory ops
# speedup vs baseline: 1.0082x; 1.0030x over previous
; DI unsigned cvt_pk_bf16(float lo, float hi) { unsigned r; asm volatile("v_cvt_pk_bf16_f32 %0, %1, %2" : "=v"(r) : "v"(lo), "v"(hi)); return r; }
;     DI void operator()(const f32x4 (&acc)[2][2][4][2], const Unit& u, int wr, int wc, int fr, int fq) const {
;     ...
;                 const int rloc = wr * 64 + fr, col0 = colb + wc * 32 + 8 * fq;
; #pragma unroll
;                 for (int ai = 0; ai < 2; ++ai)
; #pragma unroll
;                     for (int m = 0; m < 4; ++m) { bf16_t* rowp = base + (size_t)(rowb + rloc + ai * HALF + m * 16) * ld + col0;
;                         const float rs_ = ss_in ? rsqrtf(ss_in[row0 + ai * HALF + m * 16] * (1.f / DM) + EPS) : 1.f;
; #pragma unroll
;                         for (int bj = 0; bj < 2; ++bj) { const f32x4 v0 = acc[ai][bj][m][0] * rs_, v1 = acc[ai][bj][m][1] * rs_;
;                             u32x4 w; w.x = cvt_pk_bf16(v0[0], v0[1]); w.y = cvt_pk_bf16(v0[2], v0[3]); w.z = cvt_pk_bf16(v1[0], v1[1]); w.w = cvt_pk_bf16(v1[2], v1[3]);
;                             *(u32x4*)(rowp + bj * HALF) = w; } }
.LBB0_435:
	v_readlane_b32 s62, v255, 4
	v_readlane_b32 s63, v255, 5
	v_mov_b32_e32 v0, 1.0
	s_andn2_b64 vcc, exec, s[62:63]
	v_cndmask_b32_e64 v131, 0, 1, s[62:63]
	v_cmp_ne_u32_e64 s[44:45], 1, v131
	v_mov_b32_e32 v134, 1.0
	s_cbranch_vccnz .LBB0_437
	v_ashrrev_i32_e32 v131, 31, v130
	v_lshl_add_u64 v[132:133], v[130:131], 2, s[74:75]
	global_load_dword v131, v[132:133], off
	s_waitcnt vmcnt(0) lgkmcnt(0)
	v_fmamk_f32 v131, v131, 0x3a000000, v229
	v_mul_f32_e32 v132, 0x4b800000, v131
	v_cmp_gt_f32_e32 vcc, s33, v131
	s_nop 1
	v_cndmask_b32_e32 v131, v131, v132, vcc
	v_rsq_f32_e32 v131, v131
	s_nop 0
	v_mul_f32_e32 v132, 0x45800000, v131
	v_cndmask_b32_e32 v134, v131, v132, vcc
.LBB0_437:
	v_or_b32_e32 v132, s3, v248
	v_add_u32_e32 v135, s53, v251
	v_ashrrev_i32_e32 v133, 31, v132
	v_ashrrev_i32_e32 v131, 31, v135
	v_lshl_add_u64 v[132:133], v[132:133], 1, s[24:25]
	v_mul_lo_u32 v136, s16, v131
	v_mul_lo_u32 v131, s17, v135
	v_mad_u64_u32 v[138:139], s[24:25], s16, v135, 0
	v_add3_u32 v139, v139, v136, v131
	v_lshl_add_u64 v[142:143], v[138:139], 1, v[132:133]
	v_pk_mul_f32 v[140:141], v[128:129], v[134:135] op_sel_hi:[1,0]
	v_pk_mul_f32 v[138:139], v[126:127], v[134:135] op_sel_hi:[1,0]
	v_pk_mul_f32 v[144:145], v[124:125], v[134:135] op_sel_hi:[1,0]
	v_pk_mul_f32 v[146:147], v[122:123], v[134:135] op_sel_hi:[1,0]
	v_cvt_pk_bf16_f32 v138, v138, v139
	v_cvt_pk_bf16_f32 v139, v140, v141
	s_and_b64 vcc, exec, s[44:45]
	v_cvt_pk_bf16_f32 v140, v146, v147
	v_cvt_pk_bf16_f32 v141, v144, v145
	global_store_dwordx4 v[142:143], v[138:141], off
	v_pk_mul_f32 v[144:145], v[116:117], v[134:135] op_sel_hi:[1,0]
	v_pk_mul_f32 v[146:147], v[114:115], v[134:135] op_sel_hi:[1,0]
	v_pk_mul_f32 v[140:141], v[120:121], v[134:135] op_sel_hi:[1,0]
	v_pk_mul_f32 v[138:139], v[118:119], v[134:135] op_sel_hi:[1,0]
	s_nop 0
	v_cvt_pk_bf16_f32 v138, v138, v139
	v_cvt_pk_bf16_f32 v139, v140, v141
	v_cvt_pk_bf16_f32 v140, v146, v147
	v_cvt_pk_bf16_f32 v141, v144, v145
	global_store_dwordx4 v[142:143], v[138:141], off offset:256
	s_cbranch_vccnz .LBB0_439
	v_ashrrev_i32_e32 v131, 31, v130
	v_lshl_add_u64 v[138:139], v[130:131], 2, s[74:75]
	global_load_dword v0, v[138:139], off offset:64
	s_waitcnt vmcnt(0) lgkmcnt(0)
	v_fmamk_f32 v0, v0, 0x3a000000, v229
	v_mul_f32_e32 v131, 0x4b800000, v0
	v_cmp_gt_f32_e32 vcc, s33, v0
	s_nop 1
	v_cndmask_b32_e32 v0, v0, v131, vcc
	v_rsq_f32_e32 v0, v0
	s_nop 0
	v_mul_f32_e32 v131, 0x45800000, v0
	v_cndmask_b32_e32 v0, v0, v131, vcc
.LBB0_439:
	v_or_b32_e32 v131, 16, v135
	v_mul_lo_u32 v134, s17, v131
	v_mad_u64_u32 v[138:139], s[24:25], s16, v131, 0
	v_add3_u32 v139, v139, v136, v134
	v_lshl_add_u64 v[142:143], v[138:139], 1, v[132:133]
	v_pk_mul_f32 v[140:141], v[112:113], v[0:1] op_sel_hi:[1,0]
	v_pk_mul_f32 v[138:139], v[110:111], v[0:1] op_sel_hi:[1,0]
	v_pk_mul_f32 v[144:145], v[108:109], v[0:1] op_sel_hi:[1,0]
	v_pk_mul_f32 v[146:147], v[106:107], v[0:1] op_sel_hi:[1,0]
	v_cvt_pk_bf16_f32 v138, v138, v139
	v_cvt_pk_bf16_f32 v139, v140, v141
	s_and_b64 vcc, exec, s[44:45]
	v_cvt_pk_bf16_f32 v140, v146, v147
	v_cvt_pk_bf16_f32 v141, v144, v145
	global_store_dwordx4 v[142:143], v[138:141], off
	v_pk_mul_f32 v[144:145], v[100:101], v[0:1] op_sel_hi:[1,0]
	v_pk_mul_f32 v[146:147], v[98:99], v[0:1] op_sel_hi:[1,0]
	v_pk_mul_f32 v[140:141], v[104:105], v[0:1] op_sel_hi:[1,0]
	v_pk_mul_f32 v[138:139], v[102:103], v[0:1] op_sel_hi:[1,0]
	v_mov_b32_e32 v0, 1.0
	v_mov_b32_e32 v134, 1.0
	v_cvt_pk_bf16_f32 v138, v138, v139
	v_cvt_pk_bf16_f32 v139, v140, v141
	v_cvt_pk_bf16_f32 v140, v146, v147
	v_cvt_pk_bf16_f32 v141, v144, v145
	global_store_dwordx4 v[142:143], v[138:141], off offset:256
	s_cbranch_vccnz .LBB0_441
	v_ashrrev_i32_e32 v131, 31, v130
	v_lshl_add_u64 v[138:139], v[130:131], 2, s[74:75]
	global_load_dword v131, v[138:139], off offset:128
	s_waitcnt vmcnt(0) lgkmcnt(0)
	v_fmamk_f32 v131, v131, 0x3a000000, v229
	v_mul_f32_e32 v134, 0x4b800000, v131
	v_cmp_gt_f32_e32 vcc, s33, v131
	s_nop 1
	v_cndmask_b32_e32 v131, v131, v134, vcc
	v_rsq_f32_e32 v131, v131
	s_nop 0
	v_mul_f32_e32 v134, 0x45800000, v131
	v_cndmask_b32_e32 v134, v131, v134, vcc
.LBB0_441:
	v_or_b32_e32 v131, 32, v135
	v_mul_lo_u32 v137, s17, v131
	v_mad_u64_u32 v[138:139], s[24:25], s16, v131, 0
	v_add3_u32 v139, v139, v136, v137
	v_lshl_add_u64 v[142:143], v[138:139], 1, v[132:133]
	v_pk_mul_f32 v[140:141], v[96:97], v[134:135] op_sel_hi:[1,0]
	v_pk_mul_f32 v[138:139], v[94:95], v[134:135] op_sel_hi:[1,0]
	v_pk_mul_f32 v[144:145], v[92:93], v[134:135] op_sel_hi:[1,0]
	v_pk_mul_f32 v[146:147], v[90:91], v[134:135] op_sel_hi:[1,0]
	v_cvt_pk_bf16_f32 v138, v138, v139
	v_cvt_pk_bf16_f32 v139, v140, v141
	s_and_b64 vcc, exec, s[44:45]
	v_cvt_pk_bf16_f32 v140, v146, v147
	v_cvt_pk_bf16_f32 v141, v144, v145
	global_store_dwordx4 v[142:143], v[138:141], off
	v_pk_mul_f32 v[144:145], v[84:85], v[134:135] op_sel_hi:[1,0]
	v_pk_mul_f32 v[146:147], v[82:83], v[134:135] op_sel_hi:[1,0]
	v_pk_mul_f32 v[140:141], v[88:89], v[134:135] op_sel_hi:[1,0]
	v_pk_mul_f32 v[138:139], v[86:87], v[134:135] op_sel_hi:[1,0]
	s_nop 0
	v_cvt_pk_bf16_f32 v138, v138, v139
	v_cvt_pk_bf16_f32 v139, v140, v141
	v_cvt_pk_bf16_f32 v140, v146, v147
	v_cvt_pk_bf16_f32 v141, v144, v145
	global_store_dwordx4 v[142:143], v[138:141], off offset:256
	s_cbranch_vccnz .LBB0_443
	v_ashrrev_i32_e32 v131, 31, v130
	v_lshl_add_u64 v[138:139], v[130:131], 2, s[74:75]
	global_load_dword v0, v[138:139], off offset:192
	s_waitcnt vmcnt(0) lgkmcnt(0)
	v_fmamk_f32 v0, v0, 0x3a000000, v229
	v_mul_f32_e32 v131, 0x4b800000, v0
	v_cmp_gt_f32_e32 vcc, s33, v0
	s_nop 1
	v_cndmask_b32_e32 v0, v0, v131, vcc
	v_rsq_f32_e32 v0, v0
	s_nop 0
	v_mul_f32_e32 v131, 0x45800000, v0
	v_cndmask_b32_e32 v0, v0, v131, vcc
; DI unsigned cvt_pk_bf16(float lo, float hi) { unsigned r; asm volatile("v_cvt_pk_bf16_f32 %0, %1, %2" : "=v"(r) : "v"(lo), "v"(hi)); return r; }
;     DI void operator()(const f32x4 (&acc)[2][2][4][2], const Unit& u, int wr, int wc, int fr, int fq) const {
;     ...
;                     for (int m = 0; m < 4; ++m) { bf16_t* rowp = base + (size_t)(rowb + rloc + ai * HALF + m * 16) * ld + col0;
;                         const float rs_ = ss_in ? rsqrtf(ss_in[row0 + ai * HALF + m * 16] * (1.f / DM) + EPS) : 1.f;
; #pragma unroll
;                         for (int bj = 0; bj < 2; ++bj) { const f32x4 v0 = acc[ai][bj][m][0] * rs_, v1 = acc[ai][bj][m][1] * rs_;
;                             u32x4 w; w.x = cvt_pk_bf16(v0[0], v0[1]); w.y = cvt_pk_bf16(v0[2], v0[3]); w.z = cvt_pk_bf16(v1[0], v1[1]); w.w = cvt_pk_bf16(v1[2], v1[3]);
;                             *(u32x4*)(rowp + bj * HALF) = w; } }
.LBB0_443:
	v_or_b32_e32 v131, 48, v135
	v_mul_lo_u32 v134, s17, v131
	v_mad_u64_u32 v[138:139], s[24:25], s16, v131, 0
	v_add3_u32 v139, v139, v136, v134
	v_lshl_add_u64 v[140:141], v[138:139], 1, v[132:133]
	v_pk_mul_f32 v[138:139], v[80:81], v[0:1] op_sel_hi:[1,0]
	v_pk_mul_f32 v[136:137], v[78:79], v[0:1] op_sel_hi:[1,0]
	v_pk_mul_f32 v[142:143], v[76:77], v[0:1] op_sel_hi:[1,0]
	v_pk_mul_f32 v[144:145], v[74:75], v[0:1] op_sel_hi:[1,0]
	v_cvt_pk_bf16_f32 v136, v136, v137
	v_cvt_pk_bf16_f32 v137, v138, v139
	s_and_b64 vcc, exec, s[44:45]
	v_cvt_pk_bf16_f32 v138, v144, v145
	v_cvt_pk_bf16_f32 v139, v142, v143
	global_store_dwordx4 v[140:141], v[136:139], off
	v_pk_mul_f32 v[142:143], v[68:69], v[0:1] op_sel_hi:[1,0]
	v_pk_mul_f32 v[144:145], v[66:67], v[0:1] op_sel_hi:[1,0]
	v_pk_mul_f32 v[138:139], v[72:73], v[0:1] op_sel_hi:[1,0]
	v_pk_mul_f32 v[136:137], v[70:71], v[0:1] op_sel_hi:[1,0]
	v_mov_b32_e32 v0, 1.0
	v_mov_b32_e32 v134, 1.0
	v_cvt_pk_bf16_f32 v136, v136, v137
	v_cvt_pk_bf16_f32 v137, v138, v139
	v_cvt_pk_bf16_f32 v138, v144, v145
	v_cvt_pk_bf16_f32 v139, v142, v143
	global_store_dwordx4 v[140:141], v[136:139], off offset:256
	s_cbranch_vccnz .LBB0_445
	v_ashrrev_i32_e32 v131, 31, v130
	v_lshl_add_u64 v[136:137], v[130:131], 2, s[74:75]
	global_load_dword v131, v[136:137], off offset:512
	s_waitcnt vmcnt(0) lgkmcnt(0)
	v_fmamk_f32 v131, v131, 0x3a000000, v229
	v_mul_f32_e32 v134, 0x4b800000, v131
	v_cmp_gt_f32_e32 vcc, s33, v131
	s_nop 1
	v_cndmask_b32_e32 v131, v131, v134, vcc
	v_rsq_f32_e32 v131, v131
	s_nop 0
	v_mul_f32_e32 v134, 0x45800000, v131
	v_cndmask_b32_e32 v134, v131, v134, vcc
.LBB0_445:
	v_add_u32_e32 v131, 0x80, v135
	v_ashrrev_i32_e32 v136, 31, v131
	v_mul_lo_u32 v138, s16, v136
	v_mul_lo_u32 v139, s17, v131
	v_mad_u64_u32 v[136:137], s[24:25], s16, v131, 0
	v_add3_u32 v137, v137, v138, v139
	v_lshl_add_u64 v[140:141], v[136:137], 1, v[132:133]
	v_pk_mul_f32 v[138:139], v[64:65], v[134:135] op_sel_hi:[1,0]
	v_pk_mul_f32 v[136:137], v[62:63], v[134:135] op_sel_hi:[1,0]
	v_pk_mul_f32 v[142:143], v[60:61], v[134:135] op_sel_hi:[1,0]
	v_pk_mul_f32 v[144:145], v[58:59], v[134:135] op_sel_hi:[1,0]
	v_cvt_pk_bf16_f32 v136, v136, v137
	v_cvt_pk_bf16_f32 v137, v138, v139
	s_and_b64 vcc, exec, s[44:45]
	v_cvt_pk_bf16_f32 v138, v144, v145
	v_cvt_pk_bf16_f32 v139, v142, v143
	global_store_dwordx4 v[140:141], v[136:139], off
	v_pk_mul_f32 v[142:143], v[52:53], v[134:135] op_sel_hi:[1,0]
	v_pk_mul_f32 v[144:145], v[50:51], v[134:135] op_sel_hi:[1,0]
	v_pk_mul_f32 v[138:139], v[56:57], v[134:135] op_sel_hi:[1,0]
	v_pk_mul_f32 v[136:137], v[54:55], v[134:135] op_sel_hi:[1,0]
	s_nop 0
	v_cvt_pk_bf16_f32 v136, v136, v137
	v_cvt_pk_bf16_f32 v137, v138, v139
	v_cvt_pk_bf16_f32 v138, v144, v145
	v_cvt_pk_bf16_f32 v139, v142, v143
	global_store_dwordx4 v[140:141], v[136:139], off offset:256
	s_cbranch_vccnz .LBB0_447
	v_ashrrev_i32_e32 v131, 31, v130
	v_lshl_add_u64 v[136:137], v[130:131], 2, s[74:75]
	global_load_dword v0, v[136:137], off offset:576
	s_waitcnt vmcnt(0) lgkmcnt(0)
	v_fmamk_f32 v0, v0, 0x3a000000, v229
	v_mul_f32_e32 v131, 0x4b800000, v0
	v_cmp_gt_f32_e32 vcc, s33, v0
	s_nop 1
	v_cndmask_b32_e32 v0, v0, v131, vcc
	v_rsq_f32_e32 v0, v0
	s_nop 0
	v_mul_f32_e32 v131, 0x45800000, v0
	v_cndmask_b32_e32 v0, v0, v131, vcc
.LBB0_447:
	v_add_u32_e32 v131, 0x90, v135
	v_ashrrev_i32_e32 v134, 31, v131
	v_mul_lo_u32 v134, s16, v134
	v_mul_lo_u32 v138, s17, v131
	v_mad_u64_u32 v[136:137], s[24:25], s16, v131, 0
	v_add3_u32 v137, v137, v134, v138
	v_lshl_add_u64 v[140:141], v[136:137], 1, v[132:133]
	v_pk_mul_f32 v[138:139], v[48:49], v[0:1] op_sel_hi:[1,0]
	v_pk_mul_f32 v[136:137], v[46:47], v[0:1] op_sel_hi:[1,0]
	v_pk_mul_f32 v[142:143], v[44:45], v[0:1] op_sel_hi:[1,0]
	v_pk_mul_f32 v[144:145], v[42:43], v[0:1] op_sel_hi:[1,0]
	v_cvt_pk_bf16_f32 v136, v136, v137
	v_cvt_pk_bf16_f32 v137, v138, v139
	s_and_b64 vcc, exec, s[44:45]
	v_cvt_pk_bf16_f32 v138, v144, v145
	v_cvt_pk_bf16_f32 v139, v142, v143
	global_store_dwordx4 v[140:141], v[136:139], off
	v_pk_mul_f32 v[142:143], v[36:37], v[0:1] op_sel_hi:[1,0]
	v_pk_mul_f32 v[144:145], v[34:35], v[0:1] op_sel_hi:[1,0]
	v_pk_mul_f32 v[138:139], v[40:41], v[0:1] op_sel_hi:[1,0]
	v_pk_mul_f32 v[136:137], v[38:39], v[0:1] op_sel_hi:[1,0]
	v_mov_b32_e32 v0, 1.0
	v_mov_b32_e32 v134, 1.0
	v_cvt_pk_bf16_f32 v136, v136, v137
	v_cvt_pk_bf16_f32 v137, v138, v139
	v_cvt_pk_bf16_f32 v138, v144, v145
	v_cvt_pk_bf16_f32 v139, v142, v143
	global_store_dwordx4 v[140:141], v[136:139], off offset:256
	s_cbranch_vccnz .LBB0_449
	v_ashrrev_i32_e32 v131, 31, v130
	v_lshl_add_u64 v[136:137], v[130:131], 2, s[74:75]
	global_load_dword v131, v[136:137], off offset:640
	s_waitcnt vmcnt(0) lgkmcnt(0)
	v_fmamk_f32 v131, v131, 0x3a000000, v229
	v_mul_f32_e32 v134, 0x4b800000, v131
	v_cmp_gt_f32_e32 vcc, s33, v131
	s_nop 1
	v_cndmask_b32_e32 v131, v131, v134, vcc
	v_rsq_f32_e32 v131, v131
	s_nop 0
	v_mul_f32_e32 v134, 0x45800000, v131
	v_cndmask_b32_e32 v134, v131, v134, vcc
.LBB0_449:
	v_add_u32_e32 v131, 0xa0, v135
	v_ashrrev_i32_e32 v136, 31, v131
	v_mul_lo_u32 v138, s16, v136
	v_mul_lo_u32 v139, s17, v131
	v_mad_u64_u32 v[136:137], s[24:25], s16, v131, 0
	v_add3_u32 v137, v137, v138, v139
	v_lshl_add_u64 v[140:141], v[136:137], 1, v[132:133]
	v_pk_mul_f32 v[138:139], v[32:33], v[134:135] op_sel_hi:[1,0]
	v_pk_mul_f32 v[136:137], v[30:31], v[134:135] op_sel_hi:[1,0]
	v_pk_mul_f32 v[142:143], v[28:29], v[134:135] op_sel_hi:[1,0]
	v_pk_mul_f32 v[144:145], v[26:27], v[134:135] op_sel_hi:[1,0]
	v_cvt_pk_bf16_f32 v136, v136, v137
	v_cvt_pk_bf16_f32 v137, v138, v139
	s_and_b64 vcc, exec, s[44:45]
	v_cvt_pk_bf16_f32 v138, v144, v145
	v_cvt_pk_bf16_f32 v139, v142, v143
	global_store_dwordx4 v[140:141], v[136:139], off
	v_pk_mul_f32 v[142:143], v[20:21], v[134:135] op_sel_hi:[1,0]
	v_pk_mul_f32 v[144:145], v[18:19], v[134:135] op_sel_hi:[1,0]
	v_pk_mul_f32 v[138:139], v[24:25], v[134:135] op_sel_hi:[1,0]
	v_pk_mul_f32 v[136:137], v[22:23], v[134:135] op_sel_hi:[1,0]
	s_nop 0
	v_cvt_pk_bf16_f32 v136, v136, v137
	v_cvt_pk_bf16_f32 v137, v138, v139
	v_cvt_pk_bf16_f32 v138, v144, v145
	v_cvt_pk_bf16_f32 v139, v142, v143
	global_store_dwordx4 v[140:141], v[136:139], off offset:256
	s_cbranch_vccnz .LBB0_451
	v_ashrrev_i32_e32 v131, 31, v130
	v_lshl_add_u64 v[136:137], v[130:131], 2, s[74:75]
	global_load_dword v0, v[136:137], off offset:704
	s_waitcnt vmcnt(0) lgkmcnt(0)
	v_fmamk_f32 v0, v0, 0x3a000000, v229
	v_mul_f32_e32 v131, 0x4b800000, v0
	v_cmp_gt_f32_e32 vcc, s33, v0
	s_nop 1
	v_cndmask_b32_e32 v0, v0, v131, vcc
	v_rsq_f32_e32 v0, v0
	s_nop 0
	v_mul_f32_e32 v131, 0x45800000, v0
	v_cndmask_b32_e32 v0, v0, v131, vcc

; DI unsigned f2bf(float f) { unsigned u = __builtin_bit_cast(unsigned, f); return (u + 0x7fffu + ((u >> 16) & 1u)) >> 16; }
;     DI void operator()(const f32x4 (&acc)[2][2][4][2], const Unit& u, int wr, int wc, int fr, int fq) const {
;     ...
;             } else {
;                 bf16_t* base = ((u.pm * BM) >> 13) ? VTS1 : VTS0; const int ldt = SEQ, rowi = ((u.pm * BM) & (SEQ - 1)) + wr * 64 + fr, col0 = (u.pn - vt_lo) * BM + wc * 32 + 8 * fq;
; #pragma unroll
;                 for (int ai = 0; ai < 2; ++ai)
; #pragma unroll
;                     for (int m = 0; m < 4; ++m) { const int row = rowi + ai * HALF + m * 16;
;                         const float rs_ = ss_in ? rsqrtf(ss_in[row0 + ai * HALF + m * 16] * (1.f / DM) + EPS) : 1.f;
; #pragma unroll
;                         for (int bj = 0; bj < 2; ++bj)
; #pragma unroll
;                             for (int n = 0; n < 2; ++n)
; #pragma unroll
;                                 for (int j = 0; j < 4; ++j) base[(size_t)(col0 + bj * HALF + 4 * n + j) * ldt + row] = (bf16_t)f2bf(acc[ai][bj][m][n][j] * rs_); }
.LBB0_452:
	s_and_b64 vcc, exec, s[24:25]
	s_cbranch_vccz .LBB0_470
	v_readlane_b32 s16, v255, 4
	v_readlane_b32 s17, v255, 5
	v_mov_b32_e32 v164, 1.0
	s_andn2_b64 vcc, exec, s[16:17]
	v_cndmask_b32_e64 v0, 0, 1, s[16:17]
	v_cmp_ne_u32_e64 s[44:45], 1, v0
	v_ashrrev_i32_e32 v131, 31, v130
	v_mov_b32_e32 v162, 1.0
	s_cbranch_vccnz .LBB0_455
	v_lshl_add_u64 v[132:133], v[130:131], 2, s[74:75]
	global_load_dword v0, v[132:133], off
	s_waitcnt vmcnt(0) lgkmcnt(0)
	v_fmamk_f32 v0, v0, 0x3a000000, v229
	v_mul_f32_e32 v132, 0x4b800000, v0
	v_cmp_gt_f32_e32 vcc, s33, v0
	s_nop 1
	v_cndmask_b32_e32 v0, v0, v132, vcc
	v_rsq_f32_e32 v0, v0
	s_nop 0
	v_mul_f32_e32 v132, 0x45800000, v0
	v_cndmask_b32_e32 v162, v0, v132, vcc
.LBB0_455:
	v_readlane_b32 s16, v255, 2
	s_cmp_lt_u32 s76, 32
	v_readlane_b32 s17, v255, 3
	s_cselect_b32 s3, s17, s99
	s_cselect_b32 s13, s16, s98
	v_mov_b32_e32 v133, s3
	s_and_b32 s3, s12, 0x1f00
	v_add_u32_e32 v134, s3, v251
	v_mov_b32_e32 v132, s13
	v_ashrrev_i32_e32 v135, 31, v134
	v_mul_f32_e32 v0, v126, v162
	v_lshl_add_u64 v[132:133], v[134:135], 1, v[132:133]
	v_bfe_u32 v134, v0, 16, 1
	v_add3_u32 v0, v0, v134, s92
	v_lshlrev_b32_e32 v134, 14, v248
	v_lshl_or_b32 v166, s8, 22, v134
	v_mov_b32_e32 v167, v1
	v_lshl_add_u64 v[134:135], v[132:133], 0, v[166:167]
	global_store_short_d16_hi v[134:135], v0, off
	v_mul_f32_e32 v0, v127, v162
	v_bfe_u32 v136, v0, 16, 1
	v_add3_u32 v138, v0, v136, s92
	v_or_b32_e32 v0, 0x4000, v166
	v_lshl_add_u64 v[136:137], v[132:133], 0, v[0:1]
	global_store_short_d16_hi v[136:137], v138, off
	v_mul_f32_e32 v136, v128, v162
	v_bfe_u32 v137, v136, 16, 1
	v_add3_u32 v140, v136, v137, s92
	v_or_b32_e32 v136, 0x8000, v166
	v_mov_b32_e32 v137, v1
	v_lshl_add_u64 v[138:139], v[132:133], 0, v[136:137]
	global_store_short_d16_hi v[138:139], v140, off
	v_mul_f32_e32 v138, v129, v162
	v_bfe_u32 v139, v138, 16, 1
	v_add3_u32 v142, v138, v139, s92
	v_or_b32_e32 v138, 0xc000, v166
	v_mov_b32_e32 v139, v1
	v_lshl_add_u64 v[140:141], v[132:133], 0, v[138:139]
	global_store_short_d16_hi v[140:141], v142, off
	v_mul_f32_e32 v140, v122, v162
	v_bfe_u32 v141, v140, 16, 1
	v_add3_u32 v144, v140, v141, s92
	v_or_b32_e32 v140, 0x10000, v166
	v_mov_b32_e32 v141, v1
	v_lshl_add_u64 v[142:143], v[132:133], 0, v[140:141]
	global_store_short_d16_hi v[142:143], v144, off
	v_mul_f32_e32 v142, v123, v162
	v_bfe_u32 v143, v142, 16, 1
	v_add3_u32 v146, v142, v143, s92
	v_or_b32_e32 v142, 0x14000, v166
	v_mov_b32_e32 v143, v1
	v_lshl_add_u64 v[144:145], v[132:133], 0, v[142:143]
	global_store_short_d16_hi v[144:145], v146, off
	v_mul_f32_e32 v144, v124, v162
	v_bfe_u32 v145, v144, 16, 1
	v_add3_u32 v148, v144, v145, s92
	v_or_b32_e32 v144, 0x18000, v166
	v_mov_b32_e32 v145, v1
	v_lshl_add_u64 v[146:147], v[132:133], 0, v[144:145]
	global_store_short_d16_hi v[146:147], v148, off
	v_mul_f32_e32 v146, v125, v162
	v_bfe_u32 v147, v146, 16, 1
	v_add3_u32 v150, v146, v147, s92
	v_or_b32_e32 v146, 0x1c000, v166
	v_mov_b32_e32 v147, v1
	v_lshl_add_u64 v[148:149], v[132:133], 0, v[146:147]
	global_store_short_d16_hi v[148:149], v150, off
	v_mul_f32_e32 v148, v118, v162
	v_bfe_u32 v149, v148, 16, 1
	v_add3_u32 v152, v148, v149, s92
	v_or_b32_e32 v148, 0x200000, v166
	v_mov_b32_e32 v149, v1
	v_lshl_add_u64 v[150:151], v[132:133], 0, v[148:149]
	global_store_short_d16_hi v[150:151], v152, off
	v_mul_f32_e32 v150, v119, v162
	v_bfe_u32 v151, v150, 16, 1
	v_add3_u32 v154, v150, v151, s92
	v_or_b32_e32 v150, 0x204000, v166
	v_mov_b32_e32 v151, v1
	v_lshl_add_u64 v[152:153], v[132:133], 0, v[150:151]
	global_store_short_d16_hi v[152:153], v154, off
	v_mul_f32_e32 v152, v120, v162
	v_bfe_u32 v153, v152, 16, 1
	v_add3_u32 v156, v152, v153, s92
	v_or_b32_e32 v152, 0x208000, v166
	v_mov_b32_e32 v153, v1
	v_lshl_add_u64 v[154:155], v[132:133], 0, v[152:153]
	global_store_short_d16_hi v[154:155], v156, off
	v_mul_f32_e32 v154, v121, v162
	v_bfe_u32 v155, v154, 16, 1
	v_add3_u32 v158, v154, v155, s92
	v_or_b32_e32 v154, 0x20c000, v166
	v_mov_b32_e32 v155, v1
	v_lshl_add_u64 v[156:157], v[132:133], 0, v[154:155]
	global_store_short_d16_hi v[156:157], v158, off
	v_mul_f32_e32 v156, v114, v162
	v_bfe_u32 v157, v156, 16, 1
	v_add3_u32 v160, v156, v157, s92
	v_or_b32_e32 v156, 0x210000, v166
	v_mov_b32_e32 v157, v1
	v_lshl_add_u64 v[158:159], v[132:133], 0, v[156:157]
	global_store_short_d16_hi v[158:159], v160, off
	v_mul_f32_e32 v158, v115, v162
	v_bfe_u32 v159, v158, 16, 1
	v_add3_u32 v163, v158, v159, s92
	v_or_b32_e32 v158, 0x214000, v166
	v_mov_b32_e32 v159, v1
	v_lshl_add_u64 v[160:161], v[132:133], 0, v[158:159]
	global_store_short_d16_hi v[160:161], v163, off
	v_mul_f32_e32 v160, v116, v162
	v_bfe_u32 v161, v160, 16, 1
	v_add3_u32 v163, v160, v161, s92
	v_or_b32_e32 v160, 0x218000, v166
	v_mov_b32_e32 v161, v1
	v_lshl_add_u64 v[168:169], v[132:133], 0, v[160:161]
	v_mul_f32_e32 v162, v117, v162
	global_store_short_d16_hi v[168:169], v163, off
	v_bfe_u32 v163, v162, 16, 1
	v_add3_u32 v165, v162, v163, s92
	v_or_b32_e32 v162, 0x21c000, v166
	v_mov_b32_e32 v163, v1
	v_lshl_add_u64 v[166:167], v[132:133], 0, v[162:163]
	s_and_b64 vcc, exec, s[44:45]
	global_store_short_d16_hi v[166:167], v165, off
	s_cbranch_vccnz .LBB0_457
	v_lshl_add_u64 v[164:165], v[130:131], 2, s[74:75]
	global_load_dword v164, v[164:165], off offset:64
	s_waitcnt vmcnt(0) lgkmcnt(0)
	v_fmamk_f32 v164, v164, 0x3a000000, v229
	v_mul_f32_e32 v165, 0x4b800000, v164
	v_cmp_gt_f32_e32 vcc, s33, v164
	s_nop 1
	v_cndmask_b32_e32 v164, v164, v165, vcc
	v_rsq_f32_e32 v164, v164
	s_nop 0
	v_mul_f32_e32 v165, 0x45800000, v164
	v_cndmask_b32_e32 v164, v164, v165, vcc
; DI unsigned f2bf(float f) { unsigned u = __builtin_bit_cast(unsigned, f); return (u + 0x7fffu + ((u >> 16) & 1u)) >> 16; }
;     DI void operator()(const f32x4 (&acc)[2][2][4][2], const Unit& u, int wr, int wc, int fr, int fq) const {
;     ...
;                     for (int m = 0; m < 4; ++m) { const int row = rowi + ai * HALF + m * 16;
;                         const float rs_ = ss_in ? rsqrtf(ss_in[row0 + ai * HALF + m * 16] * (1.f / DM) + EPS) : 1.f;
; #pragma unroll
;                         for (int bj = 0; bj < 2; ++bj)
; #pragma unroll
;                             for (int n = 0; n < 2; ++n)
; #pragma unroll
;                                 for (int j = 0; j < 4; ++j) base[(size_t)(col0 + bj * HALF + 4 * n + j) * ldt + row] = (bf16_t)f2bf(acc[ai][bj][m][n][j] * rs_); }
.LBB0_457:
	v_mul_f32_e32 v165, v110, v164
	v_bfe_u32 v168, v165, 16, 1
	v_add3_u32 v165, v165, v168, s92
	global_store_short_d16_hi v[134:135], v165, off offset:32
	v_mul_f32_e32 v165, v111, v164
	v_lshl_add_u64 v[166:167], v[132:133], 0, 32
	v_bfe_u32 v168, v165, 16, 1
	v_add3_u32 v165, v165, v168, s92
	v_lshl_add_u64 v[168:169], v[166:167], 0, v[0:1]
	global_store_short_d16_hi v[168:169], v165, off
	v_mul_f32_e32 v165, v112, v164
	v_bfe_u32 v168, v165, 16, 1
	v_add3_u32 v165, v165, v168, s92
	v_lshl_add_u64 v[168:169], v[166:167], 0, v[136:137]
	global_store_short_d16_hi v[168:169], v165, off
	v_mul_f32_e32 v165, v113, v164
	v_bfe_u32 v168, v165, 16, 1
	v_add3_u32 v165, v165, v168, s92
	v_lshl_add_u64 v[168:169], v[166:167], 0, v[138:139]
	global_store_short_d16_hi v[168:169], v165, off
	v_mul_f32_e32 v165, v106, v164
	v_bfe_u32 v168, v165, 16, 1
	v_add3_u32 v165, v165, v168, s92
	v_lshl_add_u64 v[168:169], v[166:167], 0, v[140:141]
	global_store_short_d16_hi v[168:169], v165, off
	v_mul_f32_e32 v165, v107, v164
	v_bfe_u32 v168, v165, 16, 1
	v_add3_u32 v165, v165, v168, s92
	v_lshl_add_u64 v[168:169], v[166:167], 0, v[142:143]
	global_store_short_d16_hi v[168:169], v165, off
	v_mul_f32_e32 v165, v108, v164
	v_bfe_u32 v168, v165, 16, 1
	v_add3_u32 v165, v165, v168, s92
	v_lshl_add_u64 v[168:169], v[166:167], 0, v[144:145]
	global_store_short_d16_hi v[168:169], v165, off
	v_mul_f32_e32 v165, v109, v164
	v_bfe_u32 v168, v165, 16, 1
	v_add3_u32 v165, v165, v168, s92
	v_lshl_add_u64 v[168:169], v[166:167], 0, v[146:147]
	global_store_short_d16_hi v[168:169], v165, off
	v_mul_f32_e32 v165, v102, v164
	v_bfe_u32 v168, v165, 16, 1
	v_add3_u32 v165, v165, v168, s92
	v_lshl_add_u64 v[168:169], v[166:167], 0, v[148:149]
	global_store_short_d16_hi v[168:169], v165, off
	v_mul_f32_e32 v165, v103, v164
	v_bfe_u32 v168, v165, 16, 1
	v_add3_u32 v165, v165, v168, s92
	v_lshl_add_u64 v[168:169], v[166:167], 0, v[150:151]
	global_store_short_d16_hi v[168:169], v165, off
	v_mul_f32_e32 v165, v104, v164
	v_bfe_u32 v168, v165, 16, 1
	v_add3_u32 v165, v165, v168, s92
	v_lshl_add_u64 v[168:169], v[166:167], 0, v[152:153]
	global_store_short_d16_hi v[168:169], v165, off
	v_mul_f32_e32 v165, v105, v164
	v_bfe_u32 v168, v165, 16, 1
	v_add3_u32 v165, v165, v168, s92
	v_lshl_add_u64 v[168:169], v[166:167], 0, v[154:155]
	global_store_short_d16_hi v[168:169], v165, off
	v_mul_f32_e32 v165, v98, v164
	v_bfe_u32 v168, v165, 16, 1
	v_add3_u32 v165, v165, v168, s92
	v_lshl_add_u64 v[168:169], v[166:167], 0, v[156:157]
	global_store_short_d16_hi v[168:169], v165, off
	v_mul_f32_e32 v165, v99, v164
	v_bfe_u32 v168, v165, 16, 1
	v_add3_u32 v165, v165, v168, s92
	v_lshl_add_u64 v[168:169], v[166:167], 0, v[158:159]
	global_store_short_d16_hi v[168:169], v165, off
	v_mul_f32_e32 v165, v100, v164
	v_bfe_u32 v168, v165, 16, 1
	v_add3_u32 v165, v165, v168, s92
	v_lshl_add_u64 v[168:169], v[166:167], 0, v[160:161]
	v_mul_f32_e32 v164, v101, v164
	global_store_short_d16_hi v[168:169], v165, off
	v_bfe_u32 v165, v164, 16, 1
	v_add3_u32 v168, v164, v165, s92
	v_lshl_add_u64 v[164:165], v[166:167], 0, v[162:163]
	global_store_short_d16_hi v[164:165], v168, off
	v_mov_b32_e32 v164, 1.0
	s_and_b64 vcc, exec, s[44:45]
	v_mov_b32_e32 v165, 1.0
	s_cbranch_vccnz .LBB0_459
	v_lshl_add_u64 v[166:167], v[130:131], 2, s[74:75]
	global_load_dword v165, v[166:167], off offset:128
	s_waitcnt vmcnt(0) lgkmcnt(0)
	v_fmamk_f32 v165, v165, 0x3a000000, v229
	v_mul_f32_e32 v166, 0x4b800000, v165
	v_cmp_gt_f32_e32 vcc, s33, v165
	s_nop 1
	v_cndmask_b32_e32 v165, v165, v166, vcc
	v_rsq_f32_e32 v165, v165
	s_nop 0
	v_mul_f32_e32 v166, 0x45800000, v165
	v_cndmask_b32_e32 v165, v165, v166, vcc
.LBB0_459:
	v_mul_f32_e32 v168, v94, v165
	v_bfe_u32 v169, v168, 16, 1
	v_add3_u32 v168, v168, v169, s92
	global_store_short_d16_hi v[134:135], v168, off offset:64
	v_mul_f32_e32 v168, v95, v165
	v_lshl_add_u64 v[166:167], v[132:133], 0, 64
	v_bfe_u32 v169, v168, 16, 1
	v_add3_u32 v170, v168, v169, s92
	v_lshl_add_u64 v[168:169], v[166:167], 0, v[0:1]
	global_store_short_d16_hi v[168:169], v170, off
	v_mul_f32_e32 v168, v96, v165
	v_bfe_u32 v169, v168, 16, 1
	v_add3_u32 v170, v168, v169, s92
	v_lshl_add_u64 v[168:169], v[166:167], 0, v[136:137]
	global_store_short_d16_hi v[168:169], v170, off
	v_mul_f32_e32 v168, v97, v165
	v_bfe_u32 v169, v168, 16, 1
	v_add3_u32 v170, v168, v169, s92
	v_lshl_add_u64 v[168:169], v[166:167], 0, v[138:139]
	global_store_short_d16_hi v[168:169], v170, off
	v_mul_f32_e32 v168, v90, v165
	v_bfe_u32 v169, v168, 16, 1
	v_add3_u32 v170, v168, v169, s92
	v_lshl_add_u64 v[168:169], v[166:167], 0, v[140:141]
	global_store_short_d16_hi v[168:169], v170, off
	v_mul_f32_e32 v168, v91, v165
	v_bfe_u32 v169, v168, 16, 1
	v_add3_u32 v170, v168, v169, s92
	v_lshl_add_u64 v[168:169], v[166:167], 0, v[142:143]
	global_store_short_d16_hi v[168:169], v170, off
	v_mul_f32_e32 v168, v92, v165
	v_bfe_u32 v169, v168, 16, 1
	v_add3_u32 v170, v168, v169, s92
	v_lshl_add_u64 v[168:169], v[166:167], 0, v[144:145]
	global_store_short_d16_hi v[168:169], v170, off
	v_mul_f32_e32 v168, v93, v165
	v_bfe_u32 v169, v168, 16, 1
	v_add3_u32 v170, v168, v169, s92
	v_lshl_add_u64 v[168:169], v[166:167], 0, v[146:147]
	global_store_short_d16_hi v[168:169], v170, off
	v_mul_f32_e32 v168, v86, v165
	v_bfe_u32 v169, v168, 16, 1
	v_add3_u32 v170, v168, v169, s92
	v_lshl_add_u64 v[168:169], v[166:167], 0, v[148:149]
	global_store_short_d16_hi v[168:169], v170, off
	v_mul_f32_e32 v168, v87, v165
	v_bfe_u32 v169, v168, 16, 1
	v_add3_u32 v170, v168, v169, s92
	v_lshl_add_u64 v[168:169], v[166:167], 0, v[150:151]
	global_store_short_d16_hi v[168:169], v170, off
	v_mul_f32_e32 v168, v88, v165
	v_bfe_u32 v169, v168, 16, 1
	v_add3_u32 v170, v168, v169, s92
	v_lshl_add_u64 v[168:169], v[166:167], 0, v[152:153]
	global_store_short_d16_hi v[168:169], v170, off
	v_mul_f32_e32 v168, v89, v165
	v_bfe_u32 v169, v168, 16, 1
	v_add3_u32 v170, v168, v169, s92
	v_lshl_add_u64 v[168:169], v[166:167], 0, v[154:155]
	global_store_short_d16_hi v[168:169], v170, off
	v_mul_f32_e32 v168, v82, v165
	v_bfe_u32 v169, v168, 16, 1
	v_add3_u32 v170, v168, v169, s92
	v_lshl_add_u64 v[168:169], v[166:167], 0, v[156:157]
	global_store_short_d16_hi v[168:169], v170, off
	v_mul_f32_e32 v168, v83, v165
	v_bfe_u32 v169, v168, 16, 1
	v_add3_u32 v170, v168, v169, s92
	v_lshl_add_u64 v[168:169], v[166:167], 0, v[158:159]
	global_store_short_d16_hi v[168:169], v170, off
	v_mul_f32_e32 v168, v84, v165
	v_bfe_u32 v169, v168, 16, 1
	v_add3_u32 v170, v168, v169, s92
	v_lshl_add_u64 v[168:169], v[166:167], 0, v[160:161]
	v_mul_f32_e32 v165, v85, v165
	global_store_short_d16_hi v[168:169], v170, off
	v_bfe_u32 v168, v165, 16, 1
	v_add3_u32 v165, v165, v168, s92
	v_lshl_add_u64 v[166:167], v[166:167], 0, v[162:163]
	s_and_b64 vcc, exec, s[44:45]
	global_store_short_d16_hi v[166:167], v165, off
	s_cbranch_vccnz .LBB0_461
; DI unsigned f2bf(float f) { unsigned u = __builtin_bit_cast(unsigned, f); return (u + 0x7fffu + ((u >> 16) & 1u)) >> 16; }
;     DI void operator()(const f32x4 (&acc)[2][2][4][2], const Unit& u, int wr, int wc, int fr, int fq) const {
;     ...
;                     for (int m = 0; m < 4; ++m) { const int row = rowi + ai * HALF + m * 16;
;                         const float rs_ = ss_in ? rsqrtf(ss_in[row0 + ai * HALF + m * 16] * (1.f / DM) + EPS) : 1.f;
; #pragma unroll
;                         for (int bj = 0; bj < 2; ++bj)
; #pragma unroll
;                             for (int n = 0; n < 2; ++n)
; #pragma unroll
;                                 for (int j = 0; j < 4; ++j) base[(size_t)(col0 + bj * HALF + 4 * n + j) * ldt + row] = (bf16_t)f2bf(acc[ai][bj][m][n][j] * rs_); }
	v_lshl_add_u64 v[164:165], v[130:131], 2, s[74:75]
	global_load_dword v164, v[164:165], off offset:192
	s_waitcnt vmcnt(0) lgkmcnt(0)
	v_fmamk_f32 v164, v164, 0x3a000000, v229
	v_mul_f32_e32 v165, 0x4b800000, v164
	v_cmp_gt_f32_e32 vcc, s33, v164
	s_nop 1
	v_cndmask_b32_e32 v164, v164, v165, vcc
	v_rsq_f32_e32 v164, v164
	s_nop 0
	v_mul_f32_e32 v165, 0x45800000, v164
	v_cndmask_b32_e32 v164, v164, v165, vcc
.LBB0_461:
	v_mul_f32_e32 v165, v78, v164
	v_bfe_u32 v168, v165, 16, 1
	v_add3_u32 v165, v165, v168, s92
	s_mov_b64 s[12:13], 0x60
	global_store_short_d16_hi v[134:135], v165, off offset:96
	v_mul_f32_e32 v165, v79, v164
	v_lshl_add_u64 v[166:167], v[132:133], 0, s[12:13]
	v_bfe_u32 v168, v165, 16, 1
	v_add3_u32 v165, v165, v168, s92
	v_lshl_add_u64 v[168:169], v[166:167], 0, v[0:1]
	global_store_short_d16_hi v[168:169], v165, off
	v_mul_f32_e32 v165, v80, v164
	v_bfe_u32 v168, v165, 16, 1
	v_add3_u32 v165, v165, v168, s92
	v_lshl_add_u64 v[168:169], v[166:167], 0, v[136:137]
	global_store_short_d16_hi v[168:169], v165, off
	v_mul_f32_e32 v165, v81, v164
	v_bfe_u32 v168, v165, 16, 1
	v_add3_u32 v165, v165, v168, s92
	v_lshl_add_u64 v[168:169], v[166:167], 0, v[138:139]
	global_store_short_d16_hi v[168:169], v165, off
	v_mul_f32_e32 v165, v74, v164
	v_bfe_u32 v168, v165, 16, 1
	v_add3_u32 v165, v165, v168, s92
	v_lshl_add_u64 v[168:169], v[166:167], 0, v[140:141]
	global_store_short_d16_hi v[168:169], v165, off
	v_mul_f32_e32 v165, v75, v164
	v_bfe_u32 v168, v165, 16, 1
	v_add3_u32 v165, v165, v168, s92
	v_lshl_add_u64 v[168:169], v[166:167], 0, v[142:143]
	global_store_short_d16_hi v[168:169], v165, off
	v_mul_f32_e32 v165, v76, v164
	v_bfe_u32 v168, v165, 16, 1
	v_add3_u32 v165, v165, v168, s92
	v_lshl_add_u64 v[168:169], v[166:167], 0, v[144:145]
	global_store_short_d16_hi v[168:169], v165, off
	v_mul_f32_e32 v165, v77, v164
	v_bfe_u32 v168, v165, 16, 1
	v_add3_u32 v165, v165, v168, s92
	v_lshl_add_u64 v[168:169], v[166:167], 0, v[146:147]
	global_store_short_d16_hi v[168:169], v165, off
	v_mul_f32_e32 v165, v70, v164
	v_bfe_u32 v168, v165, 16, 1
	v_add3_u32 v165, v165, v168, s92
	v_lshl_add_u64 v[168:169], v[166:167], 0, v[148:149]
	global_store_short_d16_hi v[168:169], v165, off
	v_mul_f32_e32 v165, v71, v164
	v_bfe_u32 v168, v165, 16, 1
	v_add3_u32 v165, v165, v168, s92
	v_lshl_add_u64 v[168:169], v[166:167], 0, v[150:151]
	global_store_short_d16_hi v[168:169], v165, off
	v_mul_f32_e32 v165, v72, v164
	v_bfe_u32 v168, v165, 16, 1
	v_add3_u32 v165, v165, v168, s92
	v_lshl_add_u64 v[168:169], v[166:167], 0, v[152:153]
	global_store_short_d16_hi v[168:169], v165, off
	v_mul_f32_e32 v165, v73, v164
	v_bfe_u32 v168, v165, 16, 1
	v_add3_u32 v165, v165, v168, s92
	v_lshl_add_u64 v[168:169], v[166:167], 0, v[154:155]
	global_store_short_d16_hi v[168:169], v165, off
	v_mul_f32_e32 v165, v66, v164
	v_bfe_u32 v168, v165, 16, 1
	v_add3_u32 v165, v165, v168, s92
	v_lshl_add_u64 v[168:169], v[166:167], 0, v[156:157]
	global_store_short_d16_hi v[168:169], v165, off
	v_mul_f32_e32 v165, v67, v164
	v_bfe_u32 v168, v165, 16, 1
	v_add3_u32 v165, v165, v168, s92
	v_lshl_add_u64 v[168:169], v[166:167], 0, v[158:159]
	global_store_short_d16_hi v[168:169], v165, off
	v_mul_f32_e32 v165, v68, v164
	v_bfe_u32 v168, v165, 16, 1
	v_add3_u32 v165, v165, v168, s92
	v_lshl_add_u64 v[168:169], v[166:167], 0, v[160:161]
	v_mul_f32_e32 v164, v69, v164
	global_store_short_d16_hi v[168:169], v165, off
	v_bfe_u32 v165, v164, 16, 1
	v_add3_u32 v168, v164, v165, s92
	v_lshl_add_u64 v[164:165], v[166:167], 0, v[162:163]
	global_store_short_d16_hi v[164:165], v168, off
	v_mov_b32_e32 v164, 1.0
	s_and_b64 vcc, exec, s[44:45]
	v_mov_b32_e32 v165, 1.0
	s_cbranch_vccnz .LBB0_463
	v_lshl_add_u64 v[166:167], v[130:131], 2, s[74:75]
	global_load_dword v165, v[166:167], off offset:512
	s_waitcnt vmcnt(0) lgkmcnt(0)
	v_fmamk_f32 v165, v165, 0x3a000000, v229
	v_mul_f32_e32 v166, 0x4b800000, v165
	v_cmp_gt_f32_e32 vcc, s33, v165
	s_nop 1
	v_cndmask_b32_e32 v165, v165, v166, vcc
	v_rsq_f32_e32 v165, v165
	s_nop 0
	v_mul_f32_e32 v166, 0x45800000, v165
	v_cndmask_b32_e32 v165, v165, v166, vcc
.LBB0_463:
	v_mul_f32_e32 v168, v62, v165
	v_bfe_u32 v169, v168, 16, 1
	v_add3_u32 v168, v168, v169, s92
	s_mov_b64 s[12:13], 0x100
	global_store_short_d16_hi v[134:135], v168, off offset:256
	v_mul_f32_e32 v168, v63, v165
	v_lshl_add_u64 v[166:167], v[132:133], 0, s[12:13]
	v_bfe_u32 v169, v168, 16, 1
	v_add3_u32 v170, v168, v169, s92
	v_lshl_add_u64 v[168:169], v[166:167], 0, v[0:1]
	global_store_short_d16_hi v[168:169], v170, off
	v_mul_f32_e32 v168, v64, v165
	v_bfe_u32 v169, v168, 16, 1
	v_add3_u32 v170, v168, v169, s92
	v_lshl_add_u64 v[168:169], v[166:167], 0, v[136:137]
	global_store_short_d16_hi v[168:169], v170, off
	v_mul_f32_e32 v168, v65, v165
	v_bfe_u32 v169, v168, 16, 1
	v_add3_u32 v170, v168, v169, s92
	v_lshl_add_u64 v[168:169], v[166:167], 0, v[138:139]
	global_store_short_d16_hi v[168:169], v170, off
	v_mul_f32_e32 v168, v58, v165
	v_bfe_u32 v169, v168, 16, 1
	v_add3_u32 v170, v168, v169, s92
	v_lshl_add_u64 v[168:169], v[166:167], 0, v[140:141]
	global_store_short_d16_hi v[168:169], v170, off
	v_mul_f32_e32 v168, v59, v165
	v_bfe_u32 v169, v168, 16, 1
	v_add3_u32 v170, v168, v169, s92
	v_lshl_add_u64 v[168:169], v[166:167], 0, v[142:143]
	global_store_short_d16_hi v[168:169], v170, off
	v_mul_f32_e32 v168, v60, v165
	v_bfe_u32 v169, v168, 16, 1
	v_add3_u32 v170, v168, v169, s92
	v_lshl_add_u64 v[168:169], v[166:167], 0, v[144:145]
	global_store_short_d16_hi v[168:169], v170, off
	v_mul_f32_e32 v168, v61, v165
	v_bfe_u32 v169, v168, 16, 1
	v_add3_u32 v170, v168, v169, s92
; DI unsigned f2bf(float f) { unsigned u = __builtin_bit_cast(unsigned, f); return (u + 0x7fffu + ((u >> 16) & 1u)) >> 16; }
;     DI void operator()(const f32x4 (&acc)[2][2][4][2], const Unit& u, int wr, int wc, int fr, int fq) const {
;     ...
;                     for (int m = 0; m < 4; ++m) { const int row = rowi + ai * HALF + m * 16;
;                         const float rs_ = ss_in ? rsqrtf(ss_in[row0 + ai * HALF + m * 16] * (1.f / DM) + EPS) : 1.f;
; #pragma unroll
;                         for (int bj = 0; bj < 2; ++bj)
; #pragma unroll
;                             for (int n = 0; n < 2; ++n)
; #pragma unroll
;                                 for (int j = 0; j < 4; ++j) base[(size_t)(col0 + bj * HALF + 4 * n + j) * ldt + row] = (bf16_t)f2bf(acc[ai][bj][m][n][j] * rs_); }
	v_lshl_add_u64 v[168:169], v[166:167], 0, v[146:147]
	global_store_short_d16_hi v[168:169], v170, off
	v_mul_f32_e32 v168, v54, v165
	v_bfe_u32 v169, v168, 16, 1
	v_add3_u32 v170, v168, v169, s92
	v_lshl_add_u64 v[168:169], v[166:167], 0, v[148:149]
	global_store_short_d16_hi v[168:169], v170, off
	v_mul_f32_e32 v168, v55, v165
	v_bfe_u32 v169, v168, 16, 1
	v_add3_u32 v170, v168, v169, s92
	v_lshl_add_u64 v[168:169], v[166:167], 0, v[150:151]
	global_store_short_d16_hi v[168:169], v170, off
	v_mul_f32_e32 v168, v56, v165
	v_bfe_u32 v169, v168, 16, 1
	v_add3_u32 v170, v168, v169, s92
	v_lshl_add_u64 v[168:169], v[166:167], 0, v[152:153]
	global_store_short_d16_hi v[168:169], v170, off
	v_mul_f32_e32 v168, v57, v165
	v_bfe_u32 v169, v168, 16, 1
	v_add3_u32 v170, v168, v169, s92
	v_lshl_add_u64 v[168:169], v[166:167], 0, v[154:155]
	global_store_short_d16_hi v[168:169], v170, off
	v_mul_f32_e32 v168, v50, v165
	v_bfe_u32 v169, v168, 16, 1
	v_add3_u32 v170, v168, v169, s92
	v_lshl_add_u64 v[168:169], v[166:167], 0, v[156:157]
	global_store_short_d16_hi v[168:169], v170, off
	v_mul_f32_e32 v168, v51, v165
	v_bfe_u32 v169, v168, 16, 1
	v_add3_u32 v170, v168, v169, s92
	v_lshl_add_u64 v[168:169], v[166:167], 0, v[158:159]
	global_store_short_d16_hi v[168:169], v170, off
	v_mul_f32_e32 v168, v52, v165
	v_bfe_u32 v169, v168, 16, 1
	v_add3_u32 v170, v168, v169, s92
	v_lshl_add_u64 v[168:169], v[166:167], 0, v[160:161]
	v_mul_f32_e32 v165, v53, v165
	global_store_short_d16_hi v[168:169], v170, off
	v_bfe_u32 v168, v165, 16, 1
	v_add3_u32 v165, v165, v168, s92
	v_lshl_add_u64 v[166:167], v[166:167], 0, v[162:163]
	s_and_b64 vcc, exec, s[44:45]
	global_store_short_d16_hi v[166:167], v165, off
	s_cbranch_vccnz .LBB0_465
	v_lshl_add_u64 v[164:165], v[130:131], 2, s[74:75]
	global_load_dword v164, v[164:165], off offset:576
	s_waitcnt vmcnt(0) lgkmcnt(0)
	v_fmamk_f32 v164, v164, 0x3a000000, v229
	v_mul_f32_e32 v165, 0x4b800000, v164
	v_cmp_gt_f32_e32 vcc, s33, v164
	s_nop 1
	v_cndmask_b32_e32 v164, v164, v165, vcc
	v_rsq_f32_e32 v164, v164
	s_nop 0
	v_mul_f32_e32 v165, 0x45800000, v164
	v_cndmask_b32_e32 v164, v164, v165, vcc
.LBB0_465:
	v_mul_f32_e32 v165, v46, v164
	v_bfe_u32 v168, v165, 16, 1
	v_add3_u32 v165, v165, v168, s92
	s_mov_b64 s[12:13], 0x120
	global_store_short_d16_hi v[134:135], v165, off offset:288
	v_mul_f32_e32 v165, v47, v164
	v_lshl_add_u64 v[166:167], v[132:133], 0, s[12:13]
	v_bfe_u32 v168, v165, 16, 1
	v_add3_u32 v165, v165, v168, s92
	v_lshl_add_u64 v[168:169], v[166:167], 0, v[0:1]
	global_store_short_d16_hi v[168:169], v165, off
	v_mul_f32_e32 v165, v48, v164
	v_bfe_u32 v168, v165, 16, 1
	v_add3_u32 v165, v165, v168, s92
	v_lshl_add_u64 v[168:169], v[166:167], 0, v[136:137]
	global_store_short_d16_hi v[168:169], v165, off
	v_mul_f32_e32 v165, v49, v164
	v_bfe_u32 v168, v165, 16, 1
	v_add3_u32 v165, v165, v168, s92
	v_lshl_add_u64 v[168:169], v[166:167], 0, v[138:139]
	global_store_short_d16_hi v[168:169], v165, off
	v_mul_f32_e32 v165, v42, v164
	v_bfe_u32 v168, v165, 16, 1
	v_add3_u32 v165, v165, v168, s92
	v_lshl_add_u64 v[168:169], v[166:167], 0, v[140:141]
	global_store_short_d16_hi v[168:169], v165, off
	v_mul_f32_e32 v165, v43, v164
	v_bfe_u32 v168, v165, 16, 1
	v_add3_u32 v165, v165, v168, s92
	v_lshl_add_u64 v[168:169], v[166:167], 0, v[142:143]
	global_store_short_d16_hi v[168:169], v165, off
	v_mul_f32_e32 v165, v44, v164
	v_bfe_u32 v168, v165, 16, 1
	v_add3_u32 v165, v165, v168, s92
	v_lshl_add_u64 v[168:169], v[166:167], 0, v[144:145]
	global_store_short_d16_hi v[168:169], v165, off
	v_mul_f32_e32 v165, v45, v164
	v_bfe_u32 v168, v165, 16, 1
	v_add3_u32 v165, v165, v168, s92
	v_lshl_add_u64 v[168:169], v[166:167], 0, v[146:147]
	global_store_short_d16_hi v[168:169], v165, off
	v_mul_f32_e32 v165, v38, v164
	v_bfe_u32 v168, v165, 16, 1
	v_add3_u32 v165, v165, v168, s92
	v_lshl_add_u64 v[168:169], v[166:167], 0, v[148:149]
	global_store_short_d16_hi v[168:169], v165, off
	v_mul_f32_e32 v165, v39, v164
	v_bfe_u32 v168, v165, 16, 1
	v_add3_u32 v165, v165, v168, s92
	v_lshl_add_u64 v[168:169], v[166:167], 0, v[150:151]
	global_store_short_d16_hi v[168:169], v165, off
	v_mul_f32_e32 v165, v40, v164
	v_bfe_u32 v168, v165, 16, 1
	v_add3_u32 v165, v165, v168, s92
	v_lshl_add_u64 v[168:169], v[166:167], 0, v[152:153]
	global_store_short_d16_hi v[168:169], v165, off
	v_mul_f32_e32 v165, v41, v164
	v_bfe_u32 v168, v165, 16, 1
	v_add3_u32 v165, v165, v168, s92
	v_lshl_add_u64 v[168:169], v[166:167], 0, v[154:155]
	global_store_short_d16_hi v[168:169], v165, off
	v_mul_f32_e32 v165, v34, v164
	v_bfe_u32 v168, v165, 16, 1
	v_add3_u32 v165, v165, v168, s92
	v_lshl_add_u64 v[168:169], v[166:167], 0, v[156:157]
	global_store_short_d16_hi v[168:169], v165, off
	v_mul_f32_e32 v165, v35, v164
	v_bfe_u32 v168, v165, 16, 1
	v_add3_u32 v165, v165, v168, s92
	v_lshl_add_u64 v[168:169], v[166:167], 0, v[158:159]
	global_store_short_d16_hi v[168:169], v165, off
	v_mul_f32_e32 v165, v36, v164
	v_bfe_u32 v168, v165, 16, 1
	v_add3_u32 v165, v165, v168, s92
	v_lshl_add_u64 v[168:169], v[166:167], 0, v[160:161]
	v_mul_f32_e32 v164, v37, v164
	global_store_short_d16_hi v[168:169], v165, off
	v_bfe_u32 v165, v164, 16, 1
	v_add3_u32 v168, v164, v165, s92
	v_lshl_add_u64 v[164:165], v[166:167], 0, v[162:163]
	global_store_short_d16_hi v[164:165], v168, off
	v_mov_b32_e32 v164, 1.0
	s_and_b64 vcc, exec, s[44:45]
	v_mov_b32_e32 v165, 1.0
	s_cbranch_vccnz .LBB0_467
	v_lshl_add_u64 v[166:167], v[130:131], 2, s[74:75]
	global_load_dword v165, v[166:167], off offset:640
	s_waitcnt vmcnt(0) lgkmcnt(0)
	v_fmamk_f32 v165, v165, 0x3a000000, v229
	v_mul_f32_e32 v166, 0x4b800000, v165
	v_cmp_gt_f32_e32 vcc, s33, v165
	s_nop 1
	v_cndmask_b32_e32 v165, v165, v166, vcc
	v_rsq_f32_e32 v165, v165
	s_nop 0
	v_mul_f32_e32 v166, 0x45800000, v165
	v_cndmask_b32_e32 v165, v165, v166, vcc
; DI unsigned f2bf(float f) { unsigned u = __builtin_bit_cast(unsigned, f); return (u + 0x7fffu + ((u >> 16) & 1u)) >> 16; }
;     DI void operator()(const f32x4 (&acc)[2][2][4][2], const Unit& u, int wr, int wc, int fr, int fq) const {
;     ...
;                     for (int m = 0; m < 4; ++m) { const int row = rowi + ai * HALF + m * 16;
;                         const float rs_ = ss_in ? rsqrtf(ss_in[row0 + ai * HALF + m * 16] * (1.f / DM) + EPS) : 1.f;
; #pragma unroll
;                         for (int bj = 0; bj < 2; ++bj)
; #pragma unroll
;                             for (int n = 0; n < 2; ++n)
; #pragma unroll
;                                 for (int j = 0; j < 4; ++j) base[(size_t)(col0 + bj * HALF + 4 * n + j) * ldt + row] = (bf16_t)f2bf(acc[ai][bj][m][n][j] * rs_); }
.LBB0_467:
	v_mul_f32_e32 v168, v30, v165
	v_bfe_u32 v169, v168, 16, 1
	v_add3_u32 v168, v168, v169, s92
	s_mov_b64 s[12:13], 0x140
	global_store_short_d16_hi v[134:135], v168, off offset:320
	v_mul_f32_e32 v168, v31, v165
	v_lshl_add_u64 v[166:167], v[132:133], 0, s[12:13]
	v_bfe_u32 v169, v168, 16, 1
	v_add3_u32 v170, v168, v169, s92
	v_lshl_add_u64 v[168:169], v[166:167], 0, v[0:1]
	global_store_short_d16_hi v[168:169], v170, off
	v_mul_f32_e32 v168, v32, v165
	v_bfe_u32 v169, v168, 16, 1
	v_add3_u32 v170, v168, v169, s92
	v_lshl_add_u64 v[168:169], v[166:167], 0, v[136:137]
	global_store_short_d16_hi v[168:169], v170, off
	v_mul_f32_e32 v168, v33, v165
	v_bfe_u32 v169, v168, 16, 1
	v_add3_u32 v170, v168, v169, s92
	v_lshl_add_u64 v[168:169], v[166:167], 0, v[138:139]
	global_store_short_d16_hi v[168:169], v170, off
	v_mul_f32_e32 v168, v26, v165
	v_bfe_u32 v169, v168, 16, 1
	v_add3_u32 v170, v168, v169, s92
	v_lshl_add_u64 v[168:169], v[166:167], 0, v[140:141]
	global_store_short_d16_hi v[168:169], v170, off
	v_mul_f32_e32 v168, v27, v165
	v_bfe_u32 v169, v168, 16, 1
	v_add3_u32 v170, v168, v169, s92
	v_lshl_add_u64 v[168:169], v[166:167], 0, v[142:143]
	global_store_short_d16_hi v[168:169], v170, off
	v_mul_f32_e32 v168, v28, v165
	v_bfe_u32 v169, v168, 16, 1
	v_add3_u32 v170, v168, v169, s92
	v_lshl_add_u64 v[168:169], v[166:167], 0, v[144:145]
	global_store_short_d16_hi v[168:169], v170, off
	v_mul_f32_e32 v168, v29, v165
	v_bfe_u32 v169, v168, 16, 1
	v_add3_u32 v170, v168, v169, s92
	v_lshl_add_u64 v[168:169], v[166:167], 0, v[146:147]
	global_store_short_d16_hi v[168:169], v170, off
	v_mul_f32_e32 v168, v22, v165
	v_bfe_u32 v169, v168, 16, 1
	v_add3_u32 v170, v168, v169, s92
	v_lshl_add_u64 v[168:169], v[166:167], 0, v[148:149]
	global_store_short_d16_hi v[168:169], v170, off
	v_mul_f32_e32 v168, v23, v165
	v_bfe_u32 v169, v168, 16, 1
	v_add3_u32 v170, v168, v169, s92
	v_lshl_add_u64 v[168:169], v[166:167], 0, v[150:151]
	global_store_short_d16_hi v[168:169], v170, off
	v_mul_f32_e32 v168, v24, v165
	v_bfe_u32 v169, v168, 16, 1
	v_add3_u32 v170, v168, v169, s92
	v_lshl_add_u64 v[168:169], v[166:167], 0, v[152:153]
	global_store_short_d16_hi v[168:169], v170, off
	v_mul_f32_e32 v168, v25, v165
	v_bfe_u32 v169, v168, 16, 1
	v_add3_u32 v170, v168, v169, s92
	v_lshl_add_u64 v[168:169], v[166:167], 0, v[154:155]
	global_store_short_d16_hi v[168:169], v170, off
	v_mul_f32_e32 v168, v18, v165
	v_bfe_u32 v169, v168, 16, 1
	v_add3_u32 v170, v168, v169, s92
	v_lshl_add_u64 v[168:169], v[166:167], 0, v[156:157]
	global_store_short_d16_hi v[168:169], v170, off
	v_mul_f32_e32 v168, v19, v165
	v_bfe_u32 v169, v168, 16, 1
	v_add3_u32 v170, v168, v169, s92
	v_lshl_add_u64 v[168:169], v[166:167], 0, v[158:159]
	global_store_short_d16_hi v[168:169], v170, off
	v_mul_f32_e32 v168, v20, v165
	v_bfe_u32 v169, v168, 16, 1
	v_add3_u32 v170, v168, v169, s92
	v_lshl_add_u64 v[168:169], v[166:167], 0, v[160:161]
	v_mul_f32_e32 v165, v21, v165
	global_store_short_d16_hi v[168:169], v170, off
	v_bfe_u32 v168, v165, 16, 1
	v_add3_u32 v165, v165, v168, s92
	v_lshl_add_u64 v[166:167], v[166:167], 0, v[162:163]
	s_and_b64 vcc, exec, s[44:45]
	global_store_short_d16_hi v[166:167], v165, off
	s_cbranch_vccnz .LBB0_469
	v_lshl_add_u64 v[130:131], v[130:131], 2, s[74:75]
	global_load_dword v130, v[130:131], off offset:704
	s_waitcnt vmcnt(0) lgkmcnt(0)
	v_fmamk_f32 v130, v130, 0x3a000000, v229
	v_mul_f32_e32 v131, 0x4b800000, v130
	v_cmp_gt_f32_e32 vcc, s33, v130
	s_nop 1
	v_cndmask_b32_e32 v130, v130, v131, vcc
	v_rsq_f32_e32 v130, v130
	s_nop 0
	v_mul_f32_e32 v131, 0x45800000, v130
	v_cndmask_b32_e32 v164, v130, v131, vcc
.LBB0_469:
	s_mov_b64 s[12:13], 0x160
	v_lshl_add_u64 v[130:131], v[132:133], 0, s[12:13]
	v_mul_f32_e32 v132, v14, v164
	v_bfe_u32 v133, v132, 16, 1
	v_add3_u32 v132, v132, v133, s92
	global_store_short_d16_hi v[134:135], v132, off offset:352
	v_mul_f32_e32 v132, v15, v164
	v_bfe_u32 v133, v132, 16, 1
	v_add3_u32 v134, v132, v133, s92
	v_lshl_add_u64 v[132:133], v[130:131], 0, v[0:1]
	v_mul_f32_e32 v0, v16, v164
	global_store_short_d16_hi v[132:133], v134, off
	v_bfe_u32 v132, v0, 16, 1
	v_add3_u32 v0, v0, v132, s92
	v_lshl_add_u64 v[132:133], v[130:131], 0, v[136:137]
	global_store_short_d16_hi v[132:133], v0, off
	v_mul_f32_e32 v0, v17, v164
	v_bfe_u32 v132, v0, 16, 1
	v_add3_u32 v0, v0, v132, s92
	v_lshl_add_u64 v[132:133], v[130:131], 0, v[138:139]
	global_store_short_d16_hi v[132:133], v0, off
	v_mul_f32_e32 v0, v10, v164
	v_bfe_u32 v132, v0, 16, 1
	v_add3_u32 v0, v0, v132, s92
	v_lshl_add_u64 v[132:133], v[130:131], 0, v[140:141]
	global_store_short_d16_hi v[132:133], v0, off
	v_mul_f32_e32 v0, v11, v164
	v_bfe_u32 v132, v0, 16, 1
	v_add3_u32 v0, v0, v132, s92
	v_lshl_add_u64 v[132:133], v[130:131], 0, v[142:143]
	global_store_short_d16_hi v[132:133], v0, off
	v_mul_f32_e32 v0, v12, v164
	v_bfe_u32 v132, v0, 16, 1
	v_add3_u32 v0, v0, v132, s92
	v_lshl_add_u64 v[132:133], v[130:131], 0, v[144:145]
	global_store_short_d16_hi v[132:133], v0, off
	v_mul_f32_e32 v0, v13, v164
	v_bfe_u32 v132, v0, 16, 1
	v_add3_u32 v0, v0, v132, s92
	v_lshl_add_u64 v[132:133], v[130:131], 0, v[146:147]
	global_store_short_d16_hi v[132:133], v0, off
	v_mul_f32_e32 v0, v6, v164
	v_bfe_u32 v132, v0, 16, 1
	v_add3_u32 v0, v0, v132, s92
	v_lshl_add_u64 v[132:133], v[130:131], 0, v[148:149]
	global_store_short_d16_hi v[132:133], v0, off
	v_mul_f32_e32 v0, v7, v164
	v_bfe_u32 v132, v0, 16, 1
	v_add3_u32 v0, v0, v132, s92
	v_lshl_add_u64 v[132:133], v[130:131], 0, v[150:151]
	global_store_short_d16_hi v[132:133], v0, off
	v_mul_f32_e32 v0, v8, v164
	v_bfe_u32 v132, v0, 16, 1
	v_add3_u32 v0, v0, v132, s92
	v_lshl_add_u64 v[132:133], v[130:131], 0, v[152:153]
	global_store_short_d16_hi v[132:133], v0, off
	v_mul_f32_e32 v0, v9, v164
	v_bfe_u32 v132, v0, 16, 1
	v_add3_u32 v0, v0, v132, s92
	v_lshl_add_u64 v[132:133], v[130:131], 0, v[154:155]
	global_store_short_d16_hi v[132:133], v0, off
	v_mul_f32_e32 v0, v2, v164
	v_bfe_u32 v132, v0, 16, 1
	v_add3_u32 v0, v0, v132, s92
	v_lshl_add_u64 v[132:133], v[130:131], 0, v[156:157]
	global_store_short_d16_hi v[132:133], v0, off
	v_mul_f32_e32 v0, v3, v164
	v_bfe_u32 v132, v0, 16, 1
	v_add3_u32 v0, v0, v132, s92
	v_lshl_add_u64 v[132:133], v[130:131], 0, v[158:159]
	global_store_short_d16_hi v[132:133], v0, off
	v_mul_f32_e32 v0, v4, v164
	v_bfe_u32 v132, v0, 16, 1
	v_add3_u32 v0, v0, v132, s92
	v_lshl_add_u64 v[132:133], v[130:131], 0, v[160:161]
	global_store_short_d16_hi v[132:133], v0, off
	v_mul_f32_e32 v0, v5, v164
	v_bfe_u32 v132, v0, 16, 1
	v_add3_u32 v0, v0, v132, s92
	v_lshl_add_u64 v[130:131], v[130:131], 0, v[162:163]
	global_store_short_d16_hi v[130:131], v0, off
